# v12 with non-temporal (nt) conversion loads and stores in the scan loader waves (less L2 pollution)
# speedup vs baseline: 1.0079x; 1.0079x over previous
.Lcis_j_common:
	s_lshl_b32 s60, s57, 3
	s_lshl_b32 s52, s57, 5
	s_mul_i32 s52, s52, s50
	s_add_u32 s58, s58, s52
	s_addc_u32 s59, s59, 0
	s_lshl_b32 s52, s51, 7
	s_add_u32 s58, s58, s52
	s_addc_u32 s59, s59, 0
	s_add_u32 s52, s66, 5
	s_lshl_b32 s52, s51, s52
	s_add_u32 s64, s64, s52
	s_addc_u32 s65, s65, 0
	s_lshl_b32 s52, s50, 6
	s_add_u32 s64, s64, s52
	s_addc_u32 s65, s65, 0
	v_lshrrev_b32_e32 v222, 3, v197
	v_and_b32_e32 v223, 7, v197
	v_mul_u32_u24_e32 v216, s57, v222
	v_lshl_add_u32 v216, v223, 4, v216
	global_load_dwordx4 v[232:235], v216, s[58:59] nt
	s_add_u32 s58, s58, s60
	s_addc_u32 s59, s59, 0
	global_load_dwordx4 v[236:239], v216, s[58:59] nt
	s_add_u32 s58, s58, s60
	s_addc_u32 s59, s59, 0
	global_load_dwordx4 v[240:243], v216, s[58:59] nt
	s_add_u32 s58, s58, s60
	s_addc_u32 s59, s59, 0
	global_load_dwordx4 v[244:247], v216, s[58:59] nt
	s_cmp_eq_u32 s61, 0
	s_cbranch_scc1 .Lcis_a_done
	s_lshl_b32 s52, s50, 7
	s_add_u32 s62, s62, s52
	s_addc_u32 s63, s63, 0
	global_load_dword v248, v217, s[62:63] offset:0
	global_load_dword v249, v217, s[62:63] offset:32
	global_load_dword v250, v217, s[62:63] offset:64
	global_load_dword v251, v217, s[62:63] offset:96
	s_branch .Lcis_a_done
.Lcis_j_p:
	s_sub_u32 s51, s55, 0xa000
	s_movk_i32 s61, 2
	v_readlane_b32 s58, v224, 20
	v_readlane_b32 s59, v224, 21
	v_readlane_b32 s64, v224, 22
	v_readlane_b32 s65, v224, 23
	s_lshl_b32 s52, s51, 12
	s_add_u32 s58, s58, s52
	s_addc_u32 s59, s59, 0
	s_lshl_b32 s52, s51, 11
	s_add_u32 s64, s64, s52
	s_addc_u32 s65, s65, 0
	v_lshlrev_b32_e32 v216, 5, v197
	global_load_dwordx4 v[232:235], v216, s[58:59] nt
	global_load_dwordx4 v[236:239], v216, s[58:59] offset:16 nt
	global_load_dwordx4 v[240:243], v216, s[58:59] offset:2048 nt
	global_load_dwordx4 v[244:247], v216, s[58:59] offset:2064 nt

.Lcis_b_nogs:
	ds_write_b32 v218, v232 offset:0
	ds_write_b32 v218, v233 offset:4
	ds_write_b32 v218, v234 offset:8
	ds_write_b32 v218, v235 offset:12
	ds_write_b32 v218, v236 offset:1056
	ds_write_b32 v218, v237 offset:1060
	ds_write_b32 v218, v238 offset:1064
	ds_write_b32 v218, v239 offset:1068
	ds_write_b32 v218, v240 offset:2112
	ds_write_b32 v218, v241 offset:2116
	ds_write_b32 v218, v242 offset:2120
	ds_write_b32 v218, v243 offset:2124
	ds_write_b32 v218, v244 offset:3168
	ds_write_b32 v218, v245 offset:3172
	ds_write_b32 v218, v246 offset:3176
	ds_write_b32 v218, v247 offset:3180
	v_lshrrev_b32_e32 v222, 2, v197
	v_and_b32_e32 v223, 3, v197
	v_lshlrev_b32_e32 v220, s66, v222
	v_lshl_add_u32 v220, v223, 4, v220
	s_waitcnt lgkmcnt(0)
	ds_read2_b32 v[208:209], v219 offset0:0 offset1:33
	ds_read2_b32 v[210:211], v219 offset0:66 offset1:99
	ds_read2_b32 v[212:213], v219 offset0:132 offset1:165
	ds_read2_b32 v[214:215], v219 offset0:198 offset1:231
	s_waitcnt lgkmcnt(0)
	v_cvt_pk_bf16_f32 v208, v208, v209
	v_cvt_pk_bf16_f32 v209, v210, v211
	v_cvt_pk_bf16_f32 v210, v212, v213
	v_cvt_pk_bf16_f32 v211, v214, v215
	global_store_dwordx4 v220, v[208:211], s[64:65] nt
	s_add_u32 s64, s64, s67
	s_addc_u32 s65, s65, 0
	ds_read2_b32 v[208:209], v219 offset0:16 offset1:49
	ds_read2_b32 v[210:211], v219 offset0:82 offset1:115
	ds_read2_b32 v[212:213], v219 offset0:148 offset1:181
	ds_read2_b32 v[214:215], v219 offset0:214 offset1:247
	s_waitcnt lgkmcnt(0)
	v_cvt_pk_bf16_f32 v208, v208, v209
	v_cvt_pk_bf16_f32 v209, v210, v211
	v_cvt_pk_bf16_f32 v210, v212, v213
	v_cvt_pk_bf16_f32 v211, v214, v215
	global_store_dwordx4 v220, v[208:211], s[64:65] nt
	s_branch .Lcis_b_next
.Lcis_b_flat:
	v_cvt_pk_bf16_f32 v208, v232, v233
	v_cvt_pk_bf16_f32 v209, v234, v235
	v_cvt_pk_bf16_f32 v210, v236, v237
	v_cvt_pk_bf16_f32 v211, v238, v239
	v_cvt_pk_bf16_f32 v212, v240, v241
	v_cvt_pk_bf16_f32 v213, v242, v243
	v_cvt_pk_bf16_f32 v214, v244, v245
	v_cvt_pk_bf16_f32 v215, v246, v247
	v_lshlrev_b32_e32 v220, 4, v197
	global_store_dwordx4 v220, v[208:211], s[64:65] nt
	global_store_dwordx4 v220, v[212:215], s[64:65] offset:1024 nt
